# v112 + s_setprio 1/0 around the QK and PV MFMA clusters in the prompt attention head loop
# speedup vs baseline: 1.0042x; 1.0042x over previous
.LBB0_2056:
	v_mov_b32_e32 v96, v101
	ds_read_b128 v[0:3], v135
	ds_read_b128 v[4:7], v135 offset:32
	s_load_dwordx2 s[0:1], s[40:41], 0x80
	s_add_i32 s39, s45, s38
	s_waitcnt lgkmcnt(0)
	s_setprio 1
	v_mfma_f32_32x32x16_bf16 v[64:79], v[0:3], v[80:83], 0
	ds_read_b128 v[0:3], v135 offset:64
	s_add_u32 s0, s0, s36
	s_addc_u32 s1, s1, s37
	s_add_i32 s38, s38, 1
	s_nop 0
	v_mfma_f32_32x32x16_bf16 v[64:79], v[4:7], v[84:87], v[64:79]
	s_waitcnt lgkmcnt(0)
	v_mfma_f32_32x32x16_bf16 v[64:79], v[0:3], v[88:91], v[64:79]
	ds_read_b128 v[0:3], v135 offset:96
	s_waitcnt lgkmcnt(0)
	v_mfma_f32_32x32x16_bf16 v[64:79], v[0:3], v[92:95], v[64:79]
	ds_read_b128 v[0:3], v135 offset:4608
	s_waitcnt lgkmcnt(0)
	v_mfma_f32_32x32x16_bf16 v[48:63], v[0:3], v[80:83], 0
	ds_read_b128 v[0:3], v135 offset:4640
	s_waitcnt lgkmcnt(0)
	v_mfma_f32_32x32x16_bf16 v[48:63], v[0:3], v[84:87], v[48:63]
	ds_read_b128 v[0:3], v135 offset:4672
	s_waitcnt lgkmcnt(0)
	v_mfma_f32_32x32x16_bf16 v[48:63], v[0:3], v[88:91], v[48:63]
	ds_read_b128 v[0:3], v135 offset:4704
	s_waitcnt lgkmcnt(0)
	v_mfma_f32_32x32x16_bf16 v[48:63], v[0:3], v[92:95], v[48:63]
	ds_read_b128 v[0:3], v135 offset:9216
	s_waitcnt lgkmcnt(0)
	v_mfma_f32_32x32x16_bf16 v[32:47], v[0:3], v[80:83], 0
	ds_read_b128 v[0:3], v135 offset:9248
	s_waitcnt lgkmcnt(0)
	v_mfma_f32_32x32x16_bf16 v[32:47], v[0:3], v[84:87], v[32:47]
	ds_read_b128 v[0:3], v135 offset:9280
	s_waitcnt lgkmcnt(0)
	v_mfma_f32_32x32x16_bf16 v[32:47], v[0:3], v[88:91], v[32:47]
	ds_read_b128 v[0:3], v135 offset:9312
	s_waitcnt lgkmcnt(0)
	v_mfma_f32_32x32x16_bf16 v[32:47], v[0:3], v[92:95], v[32:47]
	ds_read_b128 v[0:3], v135 offset:13824
	s_waitcnt lgkmcnt(0)
	v_mfma_f32_32x32x16_bf16 v[16:31], v[0:3], v[80:83], 0
	ds_read_b128 v[0:3], v135 offset:13856
	s_waitcnt lgkmcnt(0)
	v_mfma_f32_32x32x16_bf16 v[16:31], v[0:3], v[84:87], v[16:31]
	ds_read_b128 v[0:3], v135 offset:13888
	s_waitcnt lgkmcnt(0)
	v_mfma_f32_32x32x16_bf16 v[16:31], v[0:3], v[88:91], v[16:31]
	ds_read_b128 v[0:3], v135 offset:13920
	s_waitcnt lgkmcnt(0)
	v_mfma_f32_32x32x16_bf16 v[16:31], v[0:3], v[92:95], v[16:31]
	ds_read_b128 v[0:3], v135 offset:18432
	s_waitcnt lgkmcnt(0)
	v_mfma_f32_32x32x16_bf16 v[0:15], v[0:3], v[80:83], 0
	ds_read_b128 v[80:83], v135 offset:18464
	s_waitcnt lgkmcnt(0)
	v_mfma_f32_32x32x16_bf16 v[0:15], v[80:83], v[84:87], v[0:15]
	ds_read_b128 v[80:83], v135 offset:18496
	s_waitcnt lgkmcnt(0)
	v_mfma_f32_32x32x16_bf16 v[0:15], v[80:83], v[88:91], v[0:15]
	ds_read_b128 v[80:83], v135 offset:18528
	s_waitcnt lgkmcnt(0)
	v_mfma_f32_32x32x16_bf16 v[0:15], v[80:83], v[92:95], v[0:15]
	s_setprio 0
	global_load_dword v80, v97, s[0:1]
	v_add_u32_e32 v94, 0x80, v96
	v_cmp_le_i32_e64 s[0:1], v100, v96
	v_cmp_gt_i32_e32 vcc, v100, v94
	s_or_b64 s[0:1], s[0:1], vcc
	v_readlane_b32 vcc_lo, v254, 37
	v_readlane_b32 vcc_hi, v254, 38
	s_or_b64 vcc, s[0:1], vcc
	v_cmp_ge_i32_e64 s[0:1], v100, v94
	v_cndmask_b32_e32 v64, v64, v200, vcc
	v_cmp_lt_i32_e32 vcc, v100, v96
	s_or_b64 s[0:1], vcc, s[0:1]
	v_readlane_b32 vcc_lo, v254, 39
	v_readlane_b32 vcc_hi, v254, 40
	s_or_b64 vcc, s[0:1], vcc
	v_cmp_gt_i32_e64 s[0:1], v104, v94
	v_cndmask_b32_e32 v65, v65, v200, vcc
	v_cmp_le_i32_e32 vcc, v104, v96
	s_or_b64 s[0:1], vcc, s[0:1]
	v_readlane_b32 vcc_lo, v254, 20
	v_readlane_b32 vcc_hi, v254, 21
	s_or_b64 vcc, s[0:1], vcc
	v_cmp_gt_i32_e64 s[0:1], v105, v94
	v_cndmask_b32_e32 v66, v66, v200, vcc
	v_cmp_le_i32_e32 vcc, v105, v96
	s_or_b64 s[0:1], vcc, s[0:1]
	v_readlane_b32 vcc_lo, v254, 18
	v_readlane_b32 vcc_hi, v254, 19
	s_or_b64 vcc, s[0:1], vcc
	v_cmp_gt_i32_e64 s[0:1], v106, v94
	v_cndmask_b32_e32 v67, v67, v200, vcc
	v_cmp_le_i32_e32 vcc, v106, v96
	s_or_b64 s[0:1], vcc, s[0:1]
	v_readlane_b32 vcc_lo, v254, 41
	v_readlane_b32 vcc_hi, v254, 42
	s_or_b64 vcc, s[0:1], vcc
	v_cmp_gt_i32_e64 s[0:1], v107, v94
	v_cndmask_b32_e32 v68, v68, v200, vcc
	v_cmp_le_i32_e32 vcc, v107, v96
	s_or_b64 s[0:1], vcc, s[0:1]
	v_readlane_b32 vcc_lo, v254, 22
	v_readlane_b32 vcc_hi, v254, 23
	s_or_b64 vcc, s[0:1], vcc
	v_cmp_gt_i32_e64 s[0:1], v108, v94
	v_cndmask_b32_e32 v69, v69, v200, vcc
	v_cmp_le_i32_e32 vcc, v108, v96
	s_or_b64 s[0:1], vcc, s[0:1]
	v_readlane_b32 vcc_lo, v254, 24
	v_readlane_b32 vcc_hi, v254, 25
	s_or_b64 vcc, s[0:1], vcc
	v_cmp_gt_i32_e64 s[0:1], v109, v94
	v_cndmask_b32_e32 v70, v70, v200, vcc
	v_cmp_le_i32_e32 vcc, v109, v96
	s_or_b64 s[0:1], vcc, s[0:1]
	v_readlane_b32 vcc_lo, v254, 26
	v_readlane_b32 vcc_hi, v254, 27
	s_or_b64 vcc, s[0:1], vcc
	v_cmp_gt_i32_e64 s[0:1], v110, v94
	v_cndmask_b32_e32 v71, v71, v200, vcc
	v_cmp_le_i32_e32 vcc, v110, v96
	s_or_b64 s[0:1], vcc, s[0:1]
	v_readlane_b32 vcc_lo, v254, 28
	v_readlane_b32 vcc_hi, v254, 29
	s_or_b64 vcc, s[0:1], vcc
	v_cmp_gt_i32_e64 s[0:1], v111, v94
	v_cndmask_b32_e32 v72, v72, v200, vcc
	v_cmp_le_i32_e32 vcc, v111, v96
	s_or_b64 s[0:1], vcc, s[0:1]
	v_readlane_b32 vcc_lo, v254, 32
	v_readlane_b32 vcc_hi, v254, 33
	s_or_b64 vcc, s[0:1], vcc
	v_cmp_gt_i32_e64 s[0:1], v112, v94
	v_cndmask_b32_e32 v73, v73, v200, vcc
	v_cmp_le_i32_e32 vcc, v112, v96
	s_or_b64 s[0:1], vcc, s[0:1]
	v_readlane_b32 vcc_lo, v254, 34
	v_readlane_b32 vcc_hi, v254, 35
	s_or_b64 vcc, s[0:1], vcc
	v_cmp_gt_i32_e64 s[0:1], v113, v94
	v_cndmask_b32_e32 v74, v74, v200, vcc
	v_cmp_le_i32_e32 vcc, v113, v96
	s_or_b64 s[0:1], vcc, s[0:1]
	v_readlane_b32 vcc_lo, v254, 5
	v_readlane_b32 vcc_hi, v254, 6
	s_or_b64 vcc, s[0:1], vcc
	v_cmp_gt_i32_e64 s[0:1], v114, v94
	v_cndmask_b32_e32 v75, v75, v200, vcc
	v_cmp_le_i32_e32 vcc, v114, v96
	s_or_b64 s[0:1], vcc, s[0:1]
	v_readlane_b32 vcc_lo, v254, 8
	v_readlane_b32 vcc_hi, v254, 9
	s_or_b64 vcc, s[0:1], vcc
	v_cmp_gt_i32_e64 s[0:1], v115, v94
	v_cndmask_b32_e32 v76, v76, v200, vcc
	v_cmp_le_i32_e32 vcc, v115, v96
	s_or_b64 s[0:1], vcc, s[0:1]
	v_readlane_b32 vcc_lo, v254, 30
	v_readlane_b32 vcc_hi, v254, 31
	s_or_b64 vcc, s[0:1], vcc
	v_cmp_gt_i32_e64 s[0:1], v116, v94
	v_cndmask_b32_e32 v77, v77, v200, vcc
	v_cmp_le_i32_e32 vcc, v116, v96
	s_or_b64 s[0:1], vcc, s[0:1]
	v_readlane_b32 vcc_lo, v254, 58
	v_readlane_b32 vcc_hi, v254, 59
	s_or_b64 vcc, s[0:1], vcc
	v_cmp_gt_i32_e64 s[0:1], v117, v94
	v_cndmask_b32_e32 v85, v78, v200, vcc
	v_cmp_le_i32_e32 vcc, v117, v96
	s_or_b64 s[0:1], vcc, s[0:1]
	v_readlane_b32 vcc_lo, v254, 60
	v_readlane_b32 vcc_hi, v254, 61
	s_or_b64 vcc, s[0:1], vcc
	v_readlane_b32 s0, v254, 62
	v_readlane_b32 s1, v254, 63
	s_waitcnt vmcnt(0)
	v_max3_f32 v81, v80, v64, v65
	v_max3_f32 v81, v81, v66, v67
	v_cndmask_b32_e64 v93, v48, v200, s[0:1]
	v_readlane_b32 s0, v255, 0
	v_readlane_b32 s1, v255, 1
	v_max3_f32 v81, v81, v68, v69
	v_max3_f32 v81, v81, v70, v71
	v_cndmask_b32_e64 v90, v49, v200, s[0:1]
	v_readlane_b32 s0, v255, 2
	v_readlane_b32 s1, v255, 3
	v_max3_f32 v81, v81, v72, v73
	v_max3_f32 v81, v81, v74, v75
	v_cndmask_b32_e64 v91, v50, v200, s[0:1]
	v_readlane_b32 s0, v255, 4
	v_readlane_b32 s1, v255, 5
	v_max3_f32 v81, v81, v76, v77
	v_cndmask_b32_e32 v92, v79, v200, vcc
	v_cndmask_b32_e64 v88, v51, v200, s[0:1]
	v_readlane_b32 s0, v255, 6
	v_readlane_b32 s1, v255, 7
	v_max3_f32 v78, v81, v85, v92
	v_max3_f32 v48, v78, v93, v90
	v_cndmask_b32_e64 v89, v52, v200, s[0:1]
	v_readlane_b32 s0, v255, 8
	v_readlane_b32 s1, v255, 9
	v_cmp_le_i32_e32 vcc, v118, v96
	v_max3_f32 v48, v48, v91, v88
	v_cndmask_b32_e64 v86, v53, v200, s[0:1]
	v_readlane_b32 s0, v255, 10
	v_readlane_b32 s1, v255, 11
	v_max3_f32 v48, v48, v89, v86
	v_cndmask_b32_e64 v52, v39, v200, s[6:7]
	v_cndmask_b32_e64 v87, v54, v200, s[0:1]
	v_readlane_b32 s0, v255, 12
	v_readlane_b32 s1, v255, 13
	v_cndmask_b32_e64 v51, v40, v200, s[50:51]
	v_cndmask_b32_e64 v50, v41, v200, s[52:53]
	v_cndmask_b32_e64 v83, v55, v200, s[0:1]
	v_readlane_b32 s0, v255, 14
	v_readlane_b32 s1, v255, 15
	v_max3_f32 v48, v48, v87, v83
	v_cndmask_b32_e64 v49, v42, v200, s[54:55]
	v_cndmask_b32_e64 v84, v56, v200, s[0:1]
	v_readlane_b32 s0, v255, 16
	v_readlane_b32 s1, v255, 17
	v_cndmask_b32_e64 v42, v45, v200, s[60:61]
	v_cndmask_b32_e64 v41, v46, v200, s[62:63]
	v_cndmask_b32_e64 v81, v57, v200, s[0:1]
	v_readlane_b32 s0, v255, 18
	v_readlane_b32 s1, v255, 19
	v_max3_f32 v48, v48, v84, v81
	v_cndmask_b32_e64 v40, v47, v200, s[64:65]
	v_cndmask_b32_e64 v82, v58, v200, s[0:1]
	v_readlane_b32 s0, v255, 20
	v_readlane_b32 s1, v255, 21
	v_cndmask_b32_e64 v39, v16, v200, s[66:67]
	s_nop 0
	v_cndmask_b32_e64 v78, v59, v200, s[0:1]
	v_readlane_b32 s0, v255, 22
	v_readlane_b32 s1, v255, 23
	v_max3_f32 v48, v48, v82, v78
	s_nop 0
	v_cndmask_b32_e64 v79, v60, v200, s[0:1]
	v_readlane_b32 s0, v255, 24
	v_readlane_b32 s1, v255, 25
	s_nop 1
	v_cndmask_b32_e64 v61, v61, v200, s[0:1]
	v_readlane_b32 s0, v255, 26
	v_readlane_b32 s1, v255, 27
	v_max3_f32 v48, v48, v79, v61
	s_nop 0
	v_cndmask_b32_e64 v62, v62, v200, s[0:1]
	v_readlane_b32 s0, v255, 28
	v_readlane_b32 s1, v255, 29
	s_nop 1
	v_cndmask_b32_e64 v59, v63, v200, s[0:1]
	v_readlane_b32 s0, v255, 30
	v_readlane_b32 s1, v255, 31
	v_max3_f32 v48, v48, v62, v59
	s_nop 0
	v_cndmask_b32_e64 v60, v32, v200, s[0:1]
	v_readlane_b32 s0, v255, 32
	v_readlane_b32 s1, v255, 33
	s_nop 1
	v_cndmask_b32_e64 v57, v33, v200, s[0:1]
	v_readlane_b32 s0, v255, 34
	v_readlane_b32 s1, v255, 35
	v_max3_f32 v32, v48, v60, v57
	v_cndmask_b32_e64 v48, v43, v200, s[56:57]
	v_cndmask_b32_e64 v58, v34, v200, s[0:1]
	v_readlane_b32 s0, v255, 36
	v_readlane_b32 s1, v255, 37
	v_cndmask_b32_e64 v43, v44, v200, s[58:59]
	v_cndmask_b32_e64 v34, v21, v200, s[76:77]
	v_cndmask_b32_e64 v55, v35, v200, s[0:1]
	v_readlane_b32 s0, v255, 38
	v_readlane_b32 s1, v255, 39
	v_max3_f32 v32, v32, v58, v55
	v_cndmask_b32_e64 v35, v20, v200, s[74:75]
	v_cndmask_b32_e64 v56, v36, v200, s[0:1]
	v_readlane_b32 s0, v255, 40
	v_readlane_b32 s1, v255, 41
	v_cndmask_b32_e64 v36, v19, v200, s[72:73]
	v_cndmask_b32_e64 v33, v22, v200, s[78:79]
	v_cndmask_b32_e64 v53, v37, v200, s[0:1]
	v_readlane_b32 s0, v255, 42
	v_readlane_b32 s1, v255, 43
	v_max3_f32 v32, v32, v56, v53
	v_cndmask_b32_e64 v37, v18, v200, s[70:71]
	v_cndmask_b32_e64 v54, v38, v200, s[0:1]
	v_cmp_gt_i32_e64 s[0:1], v100, v96
	s_or_b64 s[0:1], vcc, s[0:1]
	s_or_b64 vcc, s[0:1], s[42:43]
	v_cndmask_b32_e32 v0, v0, v200, vcc
	v_cmp_le_i32_e32 vcc, v119, v96
	v_cmp_gt_i32_e64 s[0:1], v119, v94
	s_or_b64 s[0:1], vcc, s[0:1]
	s_or_b64 vcc, s[0:1], s[4:5]
	v_cndmask_b32_e32 v1, v1, v200, vcc
	v_cmp_le_i32_e32 vcc, v120, v96
	v_cmp_gt_i32_e64 s[0:1], v120, v94
	s_or_b64 s[0:1], vcc, s[0:1]
	s_or_b64 vcc, s[0:1], s[48:49]
	v_cndmask_b32_e32 v2, v2, v200, vcc
	v_cmp_le_i32_e32 vcc, v121, v96
	v_cmp_gt_i32_e64 s[0:1], v121, v94
	s_or_b64 s[0:1], vcc, s[0:1]
	s_or_b64 vcc, s[0:1], s[8:9]
	v_cndmask_b32_e32 v3, v3, v200, vcc
	v_cmp_le_i32_e32 vcc, v122, v96
	v_cmp_gt_i32_e64 s[0:1], v122, v94
	s_or_b64 s[0:1], vcc, s[0:1]
	s_or_b64 vcc, s[0:1], s[10:11]
	v_cndmask_b32_e32 v4, v4, v200, vcc
	v_cmp_le_i32_e32 vcc, v123, v96
	v_cmp_gt_i32_e64 s[0:1], v123, v94
	s_or_b64 s[0:1], vcc, s[0:1]
	s_or_b64 vcc, s[0:1], s[12:13]
	v_cndmask_b32_e32 v5, v5, v200, vcc
	v_cmp_le_i32_e32 vcc, v124, v96
	v_cmp_gt_i32_e64 s[0:1], v124, v94
	s_or_b64 s[0:1], vcc, s[0:1]
	s_or_b64 vcc, s[0:1], s[14:15]
	v_cndmask_b32_e32 v6, v6, v200, vcc
	v_cmp_le_i32_e32 vcc, v125, v96
	v_cmp_gt_i32_e64 s[0:1], v125, v94
	s_or_b64 s[0:1], vcc, s[0:1]
	s_or_b64 vcc, s[0:1], s[16:17]
	v_cndmask_b32_e32 v7, v7, v200, vcc
	v_cmp_le_i32_e32 vcc, v126, v96
	v_cmp_gt_i32_e64 s[0:1], v126, v94
	s_or_b64 s[0:1], vcc, s[0:1]
	s_or_b64 vcc, s[0:1], s[18:19]
	v_cndmask_b32_e32 v8, v8, v200, vcc
	v_cmp_le_i32_e32 vcc, v127, v96
	v_cmp_gt_i32_e64 s[0:1], v127, v94
	s_or_b64 s[0:1], vcc, s[0:1]
	s_or_b64 vcc, s[0:1], s[20:21]
	v_max3_f32 v32, v32, v54, v52
	v_cndmask_b32_e32 v9, v9, v200, vcc
	v_cmp_le_i32_e32 vcc, v128, v96
	v_cmp_gt_i32_e64 s[0:1], v128, v94
	v_max3_f32 v32, v32, v51, v50
	s_or_b64 s[0:1], vcc, s[0:1]
	v_max3_f32 v32, v32, v49, v48
	s_or_b64 vcc, s[0:1], s[22:23]
	v_max3_f32 v32, v32, v43, v42
	v_cndmask_b32_e32 v10, v10, v200, vcc
	v_cmp_le_i32_e32 vcc, v129, v96
	v_cmp_gt_i32_e64 s[0:1], v129, v94
	v_max3_f32 v32, v32, v41, v40
	v_cndmask_b32_e64 v38, v17, v200, s[68:69]
	s_or_b64 s[0:1], vcc, s[0:1]
	v_max3_f32 v16, v32, v39, v38
	s_or_b64 vcc, s[0:1], s[24:25]
	v_max3_f32 v16, v16, v37, v36
	v_cndmask_b32_e32 v11, v11, v200, vcc
	v_cmp_le_i32_e32 vcc, v130, v96
	v_cmp_gt_i32_e64 s[0:1], v130, v94
	v_max3_f32 v16, v16, v35, v34
	v_cndmask_b32_e64 v32, v23, v200, s[80:81]
	s_or_b64 s[0:1], vcc, s[0:1]
	v_max3_f32 v16, v16, v33, v32
	v_cndmask_b32_e64 v23, v24, v200, s[82:83]
	v_cndmask_b32_e64 v22, v25, v200, s[84:85]
	s_or_b64 vcc, s[0:1], s[26:27]
	v_max3_f32 v16, v16, v23, v22
	v_cndmask_b32_e64 v21, v26, v200, s[86:87]
	v_cndmask_b32_e64 v20, v27, v200, s[88:89]
	v_cndmask_b32_e32 v12, v12, v200, vcc
	v_cmp_le_i32_e32 vcc, v131, v96
	v_cmp_gt_i32_e64 s[0:1], v131, v94
	v_max3_f32 v16, v16, v21, v20
	v_cndmask_b32_e64 v19, v28, v200, s[90:91]
	v_cndmask_b32_e64 v18, v29, v200, s[92:93]
	s_or_b64 s[0:1], vcc, s[0:1]
	v_max3_f32 v24, v16, v19, v18
	v_cndmask_b32_e64 v17, v30, v200, s[94:95]
	v_cndmask_b32_e64 v16, v31, v200, s[96:97]
	s_or_b64 vcc, s[0:1], s[28:29]
	v_max3_f32 v24, v24, v17, v16
	v_cndmask_b32_e32 v13, v13, v200, vcc
	v_cmp_le_i32_e32 vcc, v132, v96
	v_cmp_gt_i32_e64 s[0:1], v132, v94
	v_max3_f32 v24, v24, v0, v1
	s_or_b64 s[0:1], vcc, s[0:1]
	v_max3_f32 v24, v24, v2, v3
	s_or_b64 vcc, s[0:1], s[30:31]
	v_max3_f32 v24, v24, v4, v5
	v_cndmask_b32_e32 v14, v14, v200, vcc
	v_cmp_le_i32_e32 vcc, v133, v96
	v_cmp_gt_i32_e64 s[0:1], v133, v94
	v_max3_f32 v24, v24, v6, v7
	s_or_b64 s[0:1], vcc, s[0:1]
	v_max3_f32 v24, v24, v8, v9
	s_or_b64 vcc, s[0:1], s[34:35]
	v_max3_f32 v24, v24, v10, v11
	v_cndmask_b32_e32 v15, v15, v200, vcc
	v_max3_f32 v24, v24, v12, v13
	v_max3_f32 v24, v24, v14, v15
	v_mov_b32_e32 v26, v24
	v_mov_b32_e32 v226, v24
	s_nop 1
	v_permlane32_swap_b32_e32 v26, v226
	s_lshr_b32 s1, s39, 2
	s_mulk_i32 s1, 0x4080
	s_add_i32 s2, s1, 0x20400
	s_add_i32 s0, s44, s33
	s_waitcnt lgkmcnt(0)
	v_max_f32_e32 v24, v26, v226
	v_sub_f32_e32 v26, v64, v24
	v_mul_f32_e32 v26, 0x3fb8aa3b, v26
	v_sub_f32_e32 v28, v65, v24
	v_exp_f32_e32 v26, v26
	v_mul_f32_e32 v28, 0x3fb8aa3b, v28
	v_sub_f32_e32 v29, v66, v24
	v_exp_f32_e32 v28, v28
	v_mul_f32_e32 v29, 0x3fb8aa3b, v29
	v_sub_f32_e32 v30, v67, v24
	v_exp_f32_e32 v29, v29
	v_mul_f32_e32 v30, 0x3fb8aa3b, v30
	v_sub_f32_e32 v31, v68, v24
	v_exp_f32_e32 v30, v30
	v_mul_f32_e32 v31, 0x3fb8aa3b, v31
	v_sub_f32_e32 v44, v69, v24
	v_add_f32_e32 v27, 0, v26
	v_exp_f32_e32 v31, v31
	v_mul_f32_e32 v44, 0x3fb8aa3b, v44
	v_sub_f32_e32 v45, v70, v24
	v_add_f32_e32 v27, v28, v27
	v_exp_f32_e32 v44, v44
	v_mul_f32_e32 v45, 0x3fb8aa3b, v45
	v_sub_f32_e32 v46, v71, v24
	v_add_f32_e32 v27, v29, v27
	v_exp_f32_e32 v45, v45
	v_mul_f32_e32 v46, 0x3fb8aa3b, v46
	v_sub_f32_e32 v47, v72, v24
	v_add_f32_e32 v27, v30, v27
	v_exp_f32_e32 v46, v46
	v_mul_f32_e32 v47, 0x3fb8aa3b, v47
	v_sub_f32_e32 v63, v73, v24
	v_add_f32_e32 v27, v31, v27
	v_exp_f32_e32 v47, v47
	v_mul_f32_e32 v63, 0x3fb8aa3b, v63
	v_sub_f32_e32 v64, v74, v24
	v_add_f32_e32 v27, v44, v27
	v_exp_f32_e32 v63, v63
	v_mul_f32_e32 v64, 0x3fb8aa3b, v64
	v_sub_f32_e32 v65, v75, v24
	v_add_f32_e32 v27, v45, v27
	v_exp_f32_e32 v64, v64
	v_mul_f32_e32 v65, 0x3fb8aa3b, v65
	v_sub_f32_e32 v66, v76, v24
	v_add_f32_e32 v27, v46, v27
	v_exp_f32_e32 v65, v65
	v_mul_f32_e32 v66, 0x3fb8aa3b, v66
	v_sub_f32_e32 v67, v77, v24
	v_add_f32_e32 v27, v47, v27
	v_exp_f32_e32 v66, v66
	v_mul_f32_e32 v67, 0x3fb8aa3b, v67
	v_sub_f32_e32 v68, v85, v24
	v_add_f32_e32 v27, v63, v27
	v_exp_f32_e32 v67, v67
	v_mul_f32_e32 v68, 0x3fb8aa3b, v68
	v_sub_f32_e32 v69, v92, v24
	v_add_f32_e32 v27, v64, v27
	v_exp_f32_e32 v68, v68
	v_mul_f32_e32 v69, 0x3fb8aa3b, v69
	v_sub_f32_e32 v70, v93, v24
	v_add_f32_e32 v27, v65, v27
	v_exp_f32_e32 v69, v69
	v_mul_f32_e32 v70, 0x3fb8aa3b, v70
	v_sub_f32_e32 v71, v90, v24
	v_add_f32_e32 v27, v66, v27
	v_exp_f32_e32 v70, v70
	v_mul_f32_e32 v71, 0x3fb8aa3b, v71
	v_sub_f32_e32 v72, v91, v24
	v_add_f32_e32 v27, v67, v27
	v_exp_f32_e32 v71, v71
	v_mul_f32_e32 v72, 0x3fb8aa3b, v72
	v_sub_f32_e32 v73, v88, v24
	v_add_f32_e32 v27, v68, v27
	v_exp_f32_e32 v72, v72
	v_mul_f32_e32 v73, 0x3fb8aa3b, v73
	v_sub_f32_e32 v74, v89, v24
	v_add_f32_e32 v27, v69, v27
	v_exp_f32_e32 v73, v73
	v_mul_f32_e32 v74, 0x3fb8aa3b, v74
	v_sub_f32_e32 v75, v86, v24
	v_add_f32_e32 v27, v70, v27
	v_exp_f32_e32 v74, v74
	v_mul_f32_e32 v75, 0x3fb8aa3b, v75
	v_sub_f32_e32 v76, v87, v24
	v_add_f32_e32 v27, v71, v27
	v_exp_f32_e32 v75, v75
	v_mul_f32_e32 v76, 0x3fb8aa3b, v76
	v_sub_f32_e32 v77, v83, v24
	v_add_f32_e32 v27, v72, v27
	v_exp_f32_e32 v76, v76
	v_mul_f32_e32 v77, 0x3fb8aa3b, v77
	v_sub_f32_e32 v83, v84, v24
	v_add_f32_e32 v27, v73, v27
	v_exp_f32_e32 v77, v77
	v_mul_f32_e32 v83, 0x3fb8aa3b, v83
	v_sub_f32_e32 v81, v81, v24
	v_add_f32_e32 v27, v74, v27
	v_exp_f32_e32 v83, v83
	v_mul_f32_e32 v81, 0x3fb8aa3b, v81
	v_sub_f32_e32 v82, v82, v24
	v_add_f32_e32 v27, v75, v27
	v_exp_f32_e32 v81, v81
	v_mul_f32_e32 v82, 0x3fb8aa3b, v82
	v_sub_f32_e32 v78, v78, v24
	v_add_f32_e32 v27, v76, v27
	v_exp_f32_e32 v82, v82
	v_mul_f32_e32 v78, 0x3fb8aa3b, v78
	v_sub_f32_e32 v79, v79, v24
	v_add_f32_e32 v27, v77, v27
	v_exp_f32_e32 v78, v78
	v_mul_f32_e32 v79, 0x3fb8aa3b, v79
	v_sub_f32_e32 v61, v61, v24
	v_add_f32_e32 v27, v83, v27
	v_exp_f32_e32 v79, v79
	v_mul_f32_e32 v61, 0x3fb8aa3b, v61
	v_sub_f32_e32 v62, v62, v24
	v_add_f32_e32 v27, v81, v27
	v_exp_f32_e32 v61, v61
	v_mul_f32_e32 v62, 0x3fb8aa3b, v62
	v_sub_f32_e32 v59, v59, v24
	v_add_f32_e32 v27, v82, v27
	v_exp_f32_e32 v62, v62
	v_mul_f32_e32 v59, 0x3fb8aa3b, v59
	v_sub_f32_e32 v60, v60, v24
	v_add_f32_e32 v27, v78, v27
	v_exp_f32_e32 v59, v59
	v_mul_f32_e32 v60, 0x3fb8aa3b, v60
	v_sub_f32_e32 v57, v57, v24
	v_add_f32_e32 v27, v79, v27
	v_exp_f32_e32 v60, v60
	v_mul_f32_e32 v57, 0x3fb8aa3b, v57
	v_sub_f32_e32 v58, v58, v24
	v_add_f32_e32 v27, v61, v27
	v_exp_f32_e32 v57, v57
	v_mul_f32_e32 v58, 0x3fb8aa3b, v58
	v_sub_f32_e32 v55, v55, v24
	v_add_f32_e32 v27, v62, v27
	v_exp_f32_e32 v58, v58
	v_mul_f32_e32 v55, 0x3fb8aa3b, v55
	v_sub_f32_e32 v56, v56, v24
	v_add_f32_e32 v27, v59, v27
	v_exp_f32_e32 v55, v55
	v_mul_f32_e32 v56, 0x3fb8aa3b, v56
	v_sub_f32_e32 v53, v53, v24
	v_add_f32_e32 v27, v60, v27
	v_exp_f32_e32 v56, v56
	v_mul_f32_e32 v53, 0x3fb8aa3b, v53
	v_sub_f32_e32 v54, v54, v24
	v_add_f32_e32 v27, v57, v27
	v_exp_f32_e32 v53, v53
	v_mul_f32_e32 v54, 0x3fb8aa3b, v54
	v_sub_f32_e32 v52, v52, v24
	v_add_f32_e32 v27, v58, v27
	v_exp_f32_e32 v54, v54
	v_mul_f32_e32 v52, 0x3fb8aa3b, v52
	v_sub_f32_e32 v51, v51, v24
	v_add_f32_e32 v27, v55, v27
	v_exp_f32_e32 v52, v52
	v_mul_f32_e32 v51, 0x3fb8aa3b, v51
	v_sub_f32_e32 v50, v50, v24
	v_add_f32_e32 v27, v56, v27
	v_exp_f32_e32 v51, v51
	v_mul_f32_e32 v50, 0x3fb8aa3b, v50
	v_sub_f32_e32 v49, v49, v24
	v_add_f32_e32 v27, v53, v27
	v_exp_f32_e32 v50, v50
	v_mul_f32_e32 v49, 0x3fb8aa3b, v49
	v_sub_f32_e32 v48, v48, v24
	v_add_f32_e32 v27, v54, v27
	v_exp_f32_e32 v49, v49
	v_mul_f32_e32 v48, 0x3fb8aa3b, v48
	v_sub_f32_e32 v43, v43, v24
	v_add_f32_e32 v27, v52, v27
	v_exp_f32_e32 v48, v48
	v_mul_f32_e32 v43, 0x3fb8aa3b, v43
	v_sub_f32_e32 v42, v42, v24
	v_add_f32_e32 v27, v51, v27
	v_exp_f32_e32 v84, v43
	v_mul_f32_e32 v42, 0x3fb8aa3b, v42
	v_sub_f32_e32 v41, v41, v24
	v_add_f32_e32 v27, v50, v27
	v_exp_f32_e32 v85, v42
	v_mul_f32_e32 v41, 0x3fb8aa3b, v41
	v_sub_f32_e32 v40, v40, v24
	v_add_f32_e32 v27, v49, v27
	v_exp_f32_e32 v86, v41
	v_mul_f32_e32 v40, 0x3fb8aa3b, v40
	v_sub_f32_e32 v39, v39, v24
	v_add_f32_e32 v27, v48, v27
	v_exp_f32_e32 v87, v40
	v_mul_f32_e32 v39, 0x3fb8aa3b, v39
	v_sub_f32_e32 v38, v38, v24
	v_add_f32_e32 v27, v84, v27
	v_exp_f32_e32 v88, v39
	v_mul_f32_e32 v38, 0x3fb8aa3b, v38
	v_sub_f32_e32 v37, v37, v24
	v_add_f32_e32 v27, v85, v27
	v_exp_f32_e32 v89, v38
	v_mul_f32_e32 v37, 0x3fb8aa3b, v37
	v_sub_f32_e32 v36, v36, v24
	v_sub_f32_e32 v1, v1, v24
	v_add_f32_e32 v27, v86, v27
	v_exp_f32_e32 v90, v37
	v_mul_f32_e32 v36, 0x3fb8aa3b, v36
	v_sub_f32_e32 v35, v35, v24
	v_mul_f32_e32 v1, 0x3fb8aa3b, v1
	v_add_f32_e32 v27, v87, v27
	v_exp_f32_e32 v91, v36
	v_mul_f32_e32 v35, 0x3fb8aa3b, v35
	v_sub_f32_e32 v34, v34, v24
	v_exp_f32_e32 v142, v1
	v_sub_f32_e32 v1, v2, v24
	v_add_f32_e32 v27, v88, v27
	v_exp_f32_e32 v35, v35
	v_mul_f32_e32 v34, 0x3fb8aa3b, v34
	v_sub_f32_e32 v33, v33, v24
	v_mul_f32_e32 v1, 0x3fb8aa3b, v1
	v_add_f32_e32 v27, v89, v27
	v_exp_f32_e32 v92, v34
	v_mul_f32_e32 v33, 0x3fb8aa3b, v33
	v_sub_f32_e32 v32, v32, v24
	v_exp_f32_e32 v143, v1
	v_sub_f32_e32 v1, v3, v24
	v_add_f32_e32 v27, v90, v27
	v_exp_f32_e32 v33, v33
	v_mul_f32_e32 v32, 0x3fb8aa3b, v32
	v_sub_f32_e32 v23, v23, v24
	v_mul_f32_e32 v1, 0x3fb8aa3b, v1
	v_add_f32_e32 v27, v91, v27
	v_exp_f32_e32 v32, v32
	v_mul_f32_e32 v23, 0x3fb8aa3b, v23
	v_sub_f32_e32 v22, v22, v24
	v_exp_f32_e32 v144, v1
	v_sub_f32_e32 v1, v4, v24
	v_add_f32_e32 v27, v35, v27
	v_exp_f32_e32 v93, v23
	v_mul_f32_e32 v22, 0x3fb8aa3b, v22
	v_sub_f32_e32 v21, v21, v24
	v_mul_f32_e32 v1, 0x3fb8aa3b, v1
	v_add_f32_e32 v27, v92, v27
	v_exp_f32_e32 v94, v22
	v_mul_f32_e32 v21, 0x3fb8aa3b, v21
	v_sub_f32_e32 v20, v20, v24
	v_exp_f32_e32 v145, v1
	v_sub_f32_e32 v1, v5, v24
	v_add_f32_e32 v27, v33, v27
	v_exp_f32_e32 v95, v21
	v_mul_f32_e32 v20, 0x3fb8aa3b, v20
	v_sub_f32_e32 v19, v19, v24
	v_mul_f32_e32 v1, 0x3fb8aa3b, v1
	v_add_f32_e32 v27, v32, v27
	v_exp_f32_e32 v96, v20
	v_mul_f32_e32 v19, 0x3fb8aa3b, v19
	v_sub_f32_e32 v18, v18, v24
	v_exp_f32_e32 v146, v1
	v_sub_f32_e32 v1, v6, v24
	v_add_f32_e32 v23, v93, v27
	v_exp_f32_e32 v137, v19
	v_mul_f32_e32 v18, 0x3fb8aa3b, v18
	v_sub_f32_e32 v17, v17, v24
	v_mul_f32_e32 v1, 0x3fb8aa3b, v1
	v_add_f32_e32 v22, v94, v23
	v_exp_f32_e32 v138, v18
	v_mul_f32_e32 v17, 0x3fb8aa3b, v17
	v_sub_f32_e32 v16, v16, v24
	v_exp_f32_e32 v147, v1
	v_sub_f32_e32 v1, v7, v24
	v_add_f32_e32 v21, v95, v22
	v_exp_f32_e32 v139, v17
	v_mul_f32_e32 v16, 0x3fb8aa3b, v16
	v_sub_f32_e32 v0, v0, v24
	v_mul_f32_e32 v1, 0x3fb8aa3b, v1
	v_add_f32_e32 v20, v96, v21
	v_exp_f32_e32 v140, v16
	v_mul_f32_e32 v0, 0x3fb8aa3b, v0
	v_exp_f32_e32 v148, v1
	v_sub_f32_e32 v1, v8, v24
	v_add_f32_e32 v19, v137, v20
	v_exp_f32_e32 v141, v0
	v_mul_f32_e32 v1, 0x3fb8aa3b, v1
	v_add_f32_e32 v18, v138, v19
	v_exp_f32_e32 v149, v1
	v_sub_f32_e32 v1, v9, v24
	v_add_f32_e32 v17, v139, v18
	v_mul_f32_e32 v1, 0x3fb8aa3b, v1
	v_add_f32_e32 v16, v140, v17
	v_exp_f32_e32 v150, v1
	v_sub_f32_e32 v1, v10, v24
	v_add_f32_e32 v0, v141, v16
	v_mul_f32_e32 v1, 0x3fb8aa3b, v1
	v_add_f32_e32 v0, v142, v0
	v_exp_f32_e32 v151, v1
	v_sub_f32_e32 v1, v11, v24
	v_add_f32_e32 v0, v143, v0
	v_mul_f32_e32 v1, 0x3fb8aa3b, v1
	v_add_f32_e32 v0, v144, v0
	v_exp_f32_e32 v152, v1
	v_sub_f32_e32 v1, v12, v24
	v_add_f32_e32 v0, v145, v0
	v_mul_f32_e32 v1, 0x3fb8aa3b, v1
	v_add_f32_e32 v0, v146, v0
	v_exp_f32_e32 v153, v1
	v_sub_f32_e32 v1, v13, v24
	v_add_f32_e32 v0, v147, v0
	v_mul_f32_e32 v1, 0x3fb8aa3b, v1
	v_add_f32_e32 v0, v148, v0
	v_exp_f32_e32 v154, v1
	v_sub_f32_e32 v1, v14, v24
	v_add_f32_e32 v0, v149, v0
	v_mul_f32_e32 v1, 0x3fb8aa3b, v1
	v_add_f32_e32 v0, v150, v0
	v_exp_f32_e32 v155, v1
	v_sub_f32_e32 v1, v15, v24
	v_add_f32_e32 v0, v151, v0
	v_mul_f32_e32 v1, 0x3fb8aa3b, v1
	v_add_f32_e32 v0, v152, v0
	v_exp_f32_e32 v156, v1
	v_add_f32_e32 v0, v153, v0
	v_add_f32_e32 v0, v154, v0
	v_add_f32_e32 v0, v155, v0
	v_add_f32_e32 v0, v156, v0
	v_mov_b32_e32 v1, v0
	v_mov_b32_e32 v227, v0
	s_nop 1
	v_permlane32_swap_b32_e32 v1, v227
	v_cvt_pk_bf16_f32 v2, v31, v44
	v_add_u32_e32 v44, 0x9000, v136
	ds_read2_b64 v[4:7], v44 offset1:2
	ds_read2_b64 v[36:39], v44 offset0:4 offset1:6
	v_cvt_pk_bf16_f32 v3, v45, v46
	s_waitcnt lgkmcnt(2)
	v_add_f32_e32 v0, v1, v227
	v_sub_f32_e32 v1, v80, v24
	v_mul_f32_e32 v1, 0x3fb8aa3b, v1
	v_exp_f32_e32 v1, v1
	v_add_u32_e32 v45, 0xd000, v136
	v_cvt_pk_bf16_f32 v40, v47, v63
	v_cvt_pk_bf16_f32 v41, v64, v65
	v_add_f32_e32 v34, v1, v0
	v_cvt_pk_bf16_f32 v0, v26, v28
	v_cvt_pk_bf16_f32 v1, v29, v30
	v_cvt_pk_bf16_f32 v42, v66, v67
	v_cvt_pk_bf16_f32 v43, v68, v69
	s_waitcnt lgkmcnt(1)
	s_setprio 1
	v_mfma_f32_32x32x16_bf16 v[16:31], v[4:7], v[0:3], 0
	ds_read2_b64 v[4:7], v45 offset0:96 offset1:98
	s_and_b32 s0, s0, 0xc0
	s_mov_b64 vcc, s[46:47]
	v_readlane_b32 s1, v254, 36
	s_add_i32 s33, s33, 64
	v_mov_b32_e32 v203, 0
	v_lshl_add_u64 v[192:193], s[2:3], 0, v[98:99]
	v_lshlrev_b64 v[192:193], 9, v[192:193]
	v_lshl_add_u64 v[192:193], vcc, 0, v[192:193]
	s_lshl_b32 s2, s0, 1
	v_lshl_add_u64 v[192:193], v[192:193], 0, s[2:3]
	s_and_b32 s0, s38, 4
	s_or_b32 s0, s0, s1
	s_lshr_b32 s0, s0, 2
	v_lshlrev_b32_e32 v202, 1, v100
	v_lshl_add_u64 v[192:193], v[192:193], 0, v[202:203]
	s_mul_i32 s2, s0, 0x4080
	v_lshl_add_u64 v[194:195], s[2:3], 0, v[98:99]
	s_and_b32 s0, s33, 0xc0
	v_or_b32_e32 v196, s0, v134
	v_lshlrev_b64 v[194:195], 9, v[194:195]
	v_lshl_add_u64 v[194:195], vcc, 0, v[194:195]
	v_lshlrev_b32_e32 v202, 1, v196
	v_lshl_add_u64 v[194:195], v[194:195], 0, v[202:203]
	v_lshl_add_u64 v[224:225], v[192:193], 0, v[206:207]
	global_load_dwordx4 v[160:163], v[224:225], off
	global_load_dwordx4 v[164:167], v[224:225], off offset:32
	global_load_dwordx4 v[168:171], v[224:225], off offset:64
	global_load_dwordx4 v[172:175], v[224:225], off offset:96
	global_load_dwordx4 v[176:179], v[194:195], off
	global_load_dwordx4 v[180:183], v[194:195], off offset:32
	global_load_dwordx4 v[184:187], v[194:195], off offset:64
	global_load_dwordx4 v[188:191], v[194:195], off offset:96
	v_rcp_f32_e32 v34, v34
	s_waitcnt lgkmcnt(1)
	v_mfma_f32_32x32x16_bf16 v[16:31], v[36:39], v[40:43], v[16:31]
	ds_read2_b64 v[36:39], v45 offset0:100 offset1:102
	s_waitcnt lgkmcnt(1)
	v_mfma_f32_32x32x16_bf16 v[0:15], v[4:7], v[0:3], 0
	s_waitcnt lgkmcnt(0)
	v_mfma_f32_32x32x16_bf16 v[0:15], v[36:39], v[40:43], v[0:15]
	ds_read2_b64 v[40:43], v44 offset0:8 offset1:10
	v_cvt_pk_bf16_f32 v36, v70, v71
	v_cvt_pk_bf16_f32 v37, v72, v73
	v_cvt_pk_bf16_f32 v38, v74, v75
	v_cvt_pk_bf16_f32 v39, v76, v77
	s_waitcnt lgkmcnt(0)
	s_nop 0
	v_mfma_f32_32x32x16_bf16 v[16:31], v[40:43], v[36:39], v[16:31]
	ds_read2_b64 v[40:43], v45 offset0:104 offset1:106
	s_waitcnt lgkmcnt(0)
	v_mfma_f32_32x32x16_bf16 v[0:15], v[40:43], v[36:39], v[0:15]
	ds_read2_b64 v[40:43], v44 offset0:12 offset1:14
	v_cvt_pk_bf16_f32 v36, v83, v81
	v_cvt_pk_bf16_f32 v37, v82, v78
	v_cvt_pk_bf16_f32 v38, v79, v61
	v_cvt_pk_bf16_f32 v39, v62, v59
	s_waitcnt lgkmcnt(0)
	s_nop 0
	v_mfma_f32_32x32x16_bf16 v[16:31], v[40:43], v[36:39], v[16:31]
	ds_read2_b64 v[40:43], v45 offset0:108 offset1:110
	s_waitcnt lgkmcnt(0)
	v_mfma_f32_32x32x16_bf16 v[0:15], v[40:43], v[36:39], v[0:15]
	ds_read2_b64 v[40:43], v44 offset0:16 offset1:18
	v_cvt_pk_bf16_f32 v36, v60, v57
	v_cvt_pk_bf16_f32 v37, v58, v55
	v_cvt_pk_bf16_f32 v38, v56, v53
	v_cvt_pk_bf16_f32 v39, v54, v52
	s_waitcnt lgkmcnt(0)
	s_nop 0
	v_mfma_f32_32x32x16_bf16 v[16:31], v[40:43], v[36:39], v[16:31]
	ds_read2_b64 v[40:43], v45 offset0:112 offset1:114
	s_waitcnt lgkmcnt(0)
	v_mfma_f32_32x32x16_bf16 v[0:15], v[40:43], v[36:39], v[0:15]
	ds_read2_b64 v[40:43], v44 offset0:20 offset1:22
	v_cvt_pk_bf16_f32 v36, v51, v50
	v_cvt_pk_bf16_f32 v37, v49, v48
	v_cvt_pk_bf16_f32 v38, v84, v85
	v_cvt_pk_bf16_f32 v39, v86, v87
	s_waitcnt lgkmcnt(0)
	s_nop 0
	v_mfma_f32_32x32x16_bf16 v[16:31], v[40:43], v[36:39], v[16:31]
	ds_read2_b64 v[40:43], v45 offset0:116 offset1:118
	s_waitcnt lgkmcnt(0)
	v_mfma_f32_32x32x16_bf16 v[0:15], v[40:43], v[36:39], v[0:15]
	ds_read2_b64 v[40:43], v44 offset0:24 offset1:26
	v_cvt_pk_bf16_f32 v36, v88, v89
	v_cvt_pk_bf16_f32 v37, v90, v91
	v_cvt_pk_bf16_f32 v38, v35, v92
	v_cvt_pk_bf16_f32 v39, v33, v32
	s_waitcnt lgkmcnt(0)
	s_nop 0
	v_mfma_f32_32x32x16_bf16 v[16:31], v[40:43], v[36:39], v[16:31]
	ds_read2_b64 v[40:43], v45 offset0:120 offset1:122
	s_waitcnt lgkmcnt(0)
	v_mfma_f32_32x32x16_bf16 v[0:15], v[40:43], v[36:39], v[0:15]
	ds_read2_b64 v[40:43], v44 offset0:28 offset1:30
	v_cvt_pk_bf16_f32 v36, v93, v94
	v_cvt_pk_bf16_f32 v37, v95, v96
	v_cvt_pk_bf16_f32 v38, v137, v138
	v_cvt_pk_bf16_f32 v39, v139, v140
	s_waitcnt lgkmcnt(0)
	s_nop 0
	v_mfma_f32_32x32x16_bf16 v[16:31], v[40:43], v[36:39], v[16:31]
	ds_read2_b64 v[40:43], v45 offset0:124 offset1:126
	s_waitcnt lgkmcnt(0)
	v_mfma_f32_32x32x16_bf16 v[0:15], v[40:43], v[36:39], v[0:15]
	ds_read2_b64 v[40:43], v44 offset0:32 offset1:34
	v_cvt_pk_bf16_f32 v36, v141, v142
	v_cvt_pk_bf16_f32 v37, v143, v144
	v_cvt_pk_bf16_f32 v38, v145, v146
	v_cvt_pk_bf16_f32 v39, v147, v148
	s_waitcnt lgkmcnt(0)
	s_nop 0
	v_mfma_f32_32x32x16_bf16 v[16:31], v[40:43], v[36:39], v[16:31]
	ds_read2_b64 v[40:43], v45 offset0:128 offset1:130
	s_add_u32 s36, s36, 4
	s_addc_u32 s37, s37, 0
	s_mov_b64 s[0:1], 0x80
	s_cmp_eq_u32 s38, 8
	s_waitcnt lgkmcnt(0)
	v_mfma_f32_32x32x16_bf16 v[0:15], v[40:43], v[36:39], v[0:15]
	ds_read2_b64 v[40:43], v44 offset0:36 offset1:38
	v_cvt_pk_bf16_f32 v36, v149, v150
	v_cvt_pk_bf16_f32 v37, v151, v152
	v_cvt_pk_bf16_f32 v38, v153, v154
	v_cvt_pk_bf16_f32 v39, v155, v156
	s_waitcnt lgkmcnt(0)
	s_nop 0
	v_mfma_f32_32x32x16_bf16 v[16:31], v[40:43], v[36:39], v[16:31]
	ds_read2_b64 v[40:43], v45 offset0:132 offset1:134
	s_waitcnt lgkmcnt(0)
	v_mfma_f32_32x32x16_bf16 v[0:15], v[40:43], v[36:39], v[0:15]
	s_setprio 0
	s_nop 0
	s_nop 0
	s_nop 6
	v_pk_mul_f32 v[16:17], v[16:17], v[34:35] op_sel_hi:[1,0]
	v_pk_mul_f32 v[18:19], v[18:19], v[34:35] op_sel_hi:[1,0]
	s_nop 0
	v_pk_mul_f32 v[0:1], v[0:1], v[34:35] op_sel_hi:[1,0]
	v_pk_mul_f32 v[2:3], v[2:3], v[34:35] op_sel_hi:[1,0]
	v_lshl_add_u64 v[204:205], v[102:103], 0, v[206:207]
	s_waitcnt vmcnt(7)
	s_nop 1
	v_permlane32_swap_b32_e32 v160, v162
	v_permlane32_swap_b32_e32 v161, v163
	v_lshlrev_b32_e32 v50, 16, v160
	v_and_b32_e32 v51, 0xffff0000, v160
	v_lshlrev_b32_e32 v48, 16, v161
	v_and_b32_e32 v49, 0xffff0000, v161
	v_pk_mul_f32 v[16:17], v[16:17], v[50:51]
	v_pk_mul_f32 v[18:19], v[18:19], v[48:49]
	v_cvt_pk_bf16_f32 v208, v16, v17
	v_cvt_pk_bf16_f32 v209, v18, v19
	v_pk_mul_f32 v[16:17], v[20:21], v[34:35] op_sel_hi:[1,0]
	s_waitcnt vmcnt(7)
	v_lshlrev_b32_e32 v18, 16, v162
	v_and_b32_e32 v19, 0xffff0000, v162
	v_pk_mul_f32 v[16:17], v[16:17], v[18:19]
	v_pk_mul_f32 v[18:19], v[22:23], v[34:35] op_sel_hi:[1,0]
	v_lshlrev_b32_e32 v20, 16, v163
	v_and_b32_e32 v21, 0xffff0000, v163
	v_pk_mul_f32 v[18:19], v[18:19], v[20:21]
	v_cvt_pk_bf16_f32 v210, v16, v17
	v_cvt_pk_bf16_f32 v211, v18, v19
	s_nop 1
	v_permlane32_swap_b32_e32 v208, v210
	v_permlane32_swap_b32_e32 v209, v211
	global_store_dwordx4 v[204:205], v[208:211], off offset:-64
	v_pk_mul_f32 v[16:17], v[24:25], v[34:35] op_sel_hi:[1,0]
	s_waitcnt vmcnt(7)
	s_nop 1
	v_permlane32_swap_b32_e32 v164, v166
	v_permlane32_swap_b32_e32 v165, v167
	v_lshlrev_b32_e32 v18, 16, v164
	v_and_b32_e32 v19, 0xffff0000, v164
	v_pk_mul_f32 v[16:17], v[16:17], v[18:19]
	v_pk_mul_f32 v[18:19], v[26:27], v[34:35] op_sel_hi:[1,0]
	v_lshlrev_b32_e32 v20, 16, v165
	v_and_b32_e32 v21, 0xffff0000, v165
	v_pk_mul_f32 v[18:19], v[18:19], v[20:21]
	v_cvt_pk_bf16_f32 v212, v16, v17
	v_cvt_pk_bf16_f32 v213, v18, v19
	v_pk_mul_f32 v[16:17], v[28:29], v[34:35] op_sel_hi:[1,0]
	s_waitcnt vmcnt(7)
	v_lshlrev_b32_e32 v18, 16, v166
	v_and_b32_e32 v19, 0xffff0000, v166
	v_pk_mul_f32 v[16:17], v[16:17], v[18:19]
	v_pk_mul_f32 v[18:19], v[30:31], v[34:35] op_sel_hi:[1,0]
	v_lshlrev_b32_e32 v20, 16, v167
	v_and_b32_e32 v21, 0xffff0000, v167
	v_pk_mul_f32 v[18:19], v[18:19], v[20:21]
	v_cvt_pk_bf16_f32 v214, v16, v17
	v_cvt_pk_bf16_f32 v215, v18, v19
	s_nop 1
	v_permlane32_swap_b32_e32 v212, v214
	v_permlane32_swap_b32_e32 v213, v215
	global_store_dwordx4 v[204:205], v[212:215], off offset:-32
	s_waitcnt vmcnt(7)
	s_nop 1
	v_permlane32_swap_b32_e32 v168, v170
	v_permlane32_swap_b32_e32 v169, v171
	v_lshlrev_b32_e32 v16, 16, v168
	v_and_b32_e32 v17, 0xffff0000, v168
	v_pk_mul_f32 v[0:1], v[0:1], v[16:17]
	v_lshlrev_b32_e32 v16, 16, v169
	v_and_b32_e32 v17, 0xffff0000, v169
	v_pk_mul_f32 v[2:3], v[2:3], v[16:17]
	v_cvt_pk_bf16_f32 v216, v0, v1
	v_cvt_pk_bf16_f32 v217, v2, v3
	v_pk_mul_f32 v[0:1], v[4:5], v[34:35] op_sel_hi:[1,0]
	s_waitcnt vmcnt(7)
	v_lshlrev_b32_e32 v2, 16, v170
	v_and_b32_e32 v3, 0xffff0000, v170
	v_pk_mul_f32 v[0:1], v[0:1], v[2:3]
	v_pk_mul_f32 v[2:3], v[6:7], v[34:35] op_sel_hi:[1,0]
	v_lshlrev_b32_e32 v4, 16, v171
	v_and_b32_e32 v5, 0xffff0000, v171
	v_pk_mul_f32 v[2:3], v[2:3], v[4:5]
	v_cvt_pk_bf16_f32 v218, v0, v1
	v_cvt_pk_bf16_f32 v219, v2, v3
	s_nop 1
	v_permlane32_swap_b32_e32 v216, v218
	v_permlane32_swap_b32_e32 v217, v219
	global_store_dwordx4 v[204:205], v[216:219], off
	v_pk_mul_f32 v[0:1], v[8:9], v[34:35] op_sel_hi:[1,0]
	s_waitcnt vmcnt(7)
	s_nop 1
	v_permlane32_swap_b32_e32 v172, v174
	v_permlane32_swap_b32_e32 v173, v175
	v_lshlrev_b32_e32 v2, 16, v172
	v_and_b32_e32 v3, 0xffff0000, v172
	v_pk_mul_f32 v[0:1], v[0:1], v[2:3]
	v_pk_mul_f32 v[2:3], v[10:11], v[34:35] op_sel_hi:[1,0]
	v_lshlrev_b32_e32 v4, 16, v173
	v_and_b32_e32 v5, 0xffff0000, v173
	v_pk_mul_f32 v[2:3], v[2:3], v[4:5]
	v_cvt_pk_bf16_f32 v220, v0, v1
	v_cvt_pk_bf16_f32 v221, v2, v3
	v_pk_mul_f32 v[0:1], v[12:13], v[34:35] op_sel_hi:[1,0]
	s_waitcnt vmcnt(7)
	v_lshlrev_b32_e32 v2, 16, v174
	v_and_b32_e32 v3, 0xffff0000, v174
	v_pk_mul_f32 v[0:1], v[0:1], v[2:3]
	v_pk_mul_f32 v[2:3], v[14:15], v[34:35] op_sel_hi:[1,0]
	v_lshlrev_b32_e32 v4, 16, v175
	v_and_b32_e32 v5, 0xffff0000, v175
	v_pk_mul_f32 v[2:3], v[2:3], v[4:5]
	v_cvt_pk_bf16_f32 v222, v0, v1
	v_cvt_pk_bf16_f32 v223, v2, v3
	s_nop 1
	v_permlane32_swap_b32_e32 v220, v222
	v_permlane32_swap_b32_e32 v221, v223
	global_store_dwordx4 v[204:205], v[220:223], off offset:32
	v_lshl_add_u64 v[102:103], v[102:103], 0, s[0:1]
	s_waitcnt vmcnt(4)
	v_mov_b32_e32 v80, v176
	v_mov_b32_e32 v81, v177
	v_mov_b32_e32 v82, v178
	v_mov_b32_e32 v83, v179
	v_mov_b32_e32 v84, v180
	v_mov_b32_e32 v85, v181
	v_mov_b32_e32 v86, v182
	v_mov_b32_e32 v87, v183
	v_mov_b32_e32 v88, v184
	v_mov_b32_e32 v89, v185
	v_mov_b32_e32 v90, v186
	v_mov_b32_e32 v91, v187
	v_mov_b32_e32 v92, v188
	v_mov_b32_e32 v93, v189
	v_mov_b32_e32 v94, v190
	v_mov_b32_e32 v95, v191
	s_cbranch_scc0 .LBB0_2056
	v_readlane_b32 s91, v254, 17
	v_readlane_b32 s24, v254, 52
	s_mov_b32 s37, s3
	s_movk_i32 s25, 0x90
	s_branch .LBB0_1999
